# attention phase: one static s_setprio 1 for waves 4-7 (younger half; waves w and w+4 share a SIMD), reset to 0 at the phase end
# baseline (speedup 1.0000x reference)
.LBB0_846:
	s_cmp_ge_i32 s30, s94
	s_cselect_b64 s[2:3], -1, 0
	s_and_b64 s[0:1], s[2:3], s[0:1]
	s_andn2_b64 vcc, exec, s[0:1]
	s_cbranch_vccnz .LBB0_924
	v_readlane_b32 s2, v254, 1
	v_readlane_b32 s82, v254, 0
	v_mov_b32_e32 v0, v182
	v_readlane_b32 s3, v254, 2
	s_load_dwordx2 s[0:1], s[2:3], 0xe0
	v_readfirstlane_b32 s28, v0
	v_and_b32_e32 v120, 63, v0
	s_ashr_i32 s30, s28, 6
	v_and_b32_e32 v121, 15, v0
	s_cmpk_gt_i32 s82, 0x407
	v_and_b32_e32 v125, 48, v0
	v_or_b32_e32 v176, 48, v120
	s_cbranch_scc1 .LBB0_888
	s_waitcnt lgkmcnt(0)
	s_cmp_gt_u32 s28, 255
	s_cbranch_scc0 .Lprio_attn
	s_setprio 1
.Lprio_attn:
	s_add_u32 s79, s0, 0xc840000
	s_addc_u32 s33, s1, 0
	s_add_u32 s60, s0, 0xe880000
	s_addc_u32 s61, s1, 0
	s_add_u32 s62, s0, 0x108c0000
	s_addc_u32 s63, s1, 0
	s_add_u32 s64, s0, 0x400000
	s_addc_u32 s65, s1, 0
	s_cmp_gt_u32 s28, 63
	v_lshrrev_b32_e32 v1, 1, v120
	s_cselect_b64 s[66:67], -1, 0
	s_lshl_b32 s88, s30, 5
	v_and_b32_e32 v122, 24, v1
	v_and_b32_e32 v1, 7, v0
	s_or_b32 s36, s88, 16
	s_add_i32 s88, s88, 47
	v_lshlrev_b32_e32 v4, 4, v1
	v_mov_b32_e32 v5, v145
	v_mov_b32_e32 v123, v145
	v_ashrrev_i32_e32 v178, 3, v0
	s_add_u32 s89, s0, 0x90000
	v_lshlrev_b32_e32 v124, 3, v1
	v_cmp_gt_u32_e64 s[40:41], 2, v1
	v_lshlrev_b32_e32 v3, 3, v0
	s_movk_i32 s4, 0x90
	v_lshl_add_u64 v[126:127], s[60:61], 0, v[4:5]
	v_lshlrev_b32_e32 v1, 1, v120
	v_and_b32_e32 v5, 3, v0
	v_lshlrev_b32_e32 v0, 1, v0
	s_addc_u32 s90, s1, 0
	v_and_or_b32 v203, v3, 8, v191
	v_mul_lo_u32 v3, v178, s4
	v_and_or_b32 v1, v1, 24, v5
	v_lshl_add_u64 v[6:7], s[0:1], 0, v[122:123]
	s_mov_b64 s[28:29], 0x1aa00000
	v_and_b32_e32 v144, 0x60, v0
	s_add_u32 s91, s0, 0xa0000
	v_lshlrev_b32_e32 v2, 6, v120
	v_add_u32_e32 v3, 0, v3
	v_add_u32_e32 v5, 0, v125
	v_lshl_add_u64 v[128:129], v[6:7], 0, s[28:29]
	v_mad_u32_u24 v6, v1, s4, 0
	v_mul_u32_u24_e32 v7, 0x90, v121
	v_mul_u32_u24_e32 v8, 0x90, v176
	v_lshl_add_u64 v[0:1], s[0:1], 0, v[144:145]
	s_mov_b64 s[28:29], 0x4000c0
	v_or_b32_e32 v177, 0x8000, v121
	s_addc_u32 s92, s1, 0
	v_cmp_gt_i32_e64 s[38:39], 16, v178
	v_subrev_u32_e32 v179, 64, v178
	v_and_or_b32 v180, v178, 15, v191
	v_or_b32_e32 v181, 0xffffffc0, v124
	v_cmp_eq_u32_e64 s[42:43], 0, v120
	v_cmp_gt_u32_e64 s[44:45], 2, v120
	v_cmp_gt_u32_e64 s[46:47], 4, v120
	v_cmp_gt_u32_e64 s[48:49], 8, v120
	v_cmp_gt_u32_e64 s[50:51], 16, v120
	v_cmp_gt_u32_e64 s[52:53], 32, v120
	v_or_b32_e32 v123, 32, v122
	v_or_b32_e32 v204, 1, v122
	v_or_b32_e32 v205, 2, v122
	v_or_b32_e32 v206, 3, v122
	v_or_b32_e32 v207, 4, v122
	v_or_b32_e32 v208, 5, v122
	v_or_b32_e32 v209, 6, v122
	v_or_b32_e32 v210, 7, v122
	v_or_b32_e32 v211, 33, v122
	v_or_b32_e32 v212, 34, v122
	v_or_b32_e32 v213, 35, v122
	v_or_b32_e32 v214, 36, v122
	v_or_b32_e32 v215, 37, v122
	v_or_b32_e32 v216, 38, v122
	v_or_b32_e32 v217, 39, v122
	v_lshl_add_u64 v[130:131], v[0:1], 0, s[28:29]
	v_lshlrev_b32_e32 v144, 1, v122
	v_lshlrev_b32_e32 v218, 2, v120
	v_lshlrev_b32_e32 v219, 2, v2
	v_add_u32_e32 v220, v3, v4
	v_add_u32_e32 v221, v6, v125
	v_add_u32_e32 v222, v5, v7
	v_add_u32_e32 v223, v5, v8
	s_mov_b32 s93, s82
	s_branch .LBB0_850

.LBB0_888:
	s_setprio 0
	s_lshl_b32 s4, s82, 3
	s_add_i32 s28, s4, s30
	v_readlane_b32 s94, v255, 9
	v_readlane_b32 s62, v254, 61
	v_readlane_b32 s64, v254, 63
	v_readlane_b32 s66, v255, 1
	v_readlane_b32 s8, v255, 11
	v_readlane_b32 s90, v255, 3
	v_readlane_b32 s60, v255, 5
	v_readlane_b32 s68, v255, 7
	s_cmpk_gt_i32 s28, 0x7ff
	v_readlane_b32 s95, v255, 10
	v_readlane_b32 s63, v254, 62
	v_readlane_b32 s65, v255, 0
	v_readlane_b32 s67, v255, 2
	v_readlane_b32 s9, v255, 12
	v_readlane_b32 s91, v255, 4
	v_readlane_b32 s61, v255, 6
	v_readlane_b32 s69, v255, 8
	s_waitcnt vmcnt(0) lgkmcnt(0)
	s_barrier
	s_cbranch_scc1 .LBB0_924
	s_mulk_i32 s30, 0x3800
	s_add_i32 s30, s30, 0
	s_add_u32 s4, s0, 0x1cac1000
	s_addc_u32 s5, s1, 0
	s_add_u32 s34, s0, 0xa800000
	v_lshlrev_b32_e32 v0, 2, v120
	v_mov_b32_e32 v1, v145
	s_load_dwordx16 s[60:75], s[2:3], 0x50
	s_addc_u32 s35, s1, 0
	v_lshl_add_u64 v[0:1], s[0:1], 0, v[0:1]
	s_mov_b64 s[0:1], 0x600000
	v_lshl_add_u64 v[36:37], v[0:1], 0, s[0:1]
	v_bfrev_b32_e32 v0, 64
	v_lshrrev_b32_e32 v6, 4, v120
	v_readlane_b32 s2, v254, 56
	v_lshl_or_b32 v0, v121, 10, v0
	v_mov_b32_e32 v1, v145
	v_and_b32_e32 v7, 64, v183
	s_lshl_b32 s84, s2, 9
	v_lshl_add_u64 v[2:3], s[34:35], 0, v[0:1]
	v_lshlrev_b32_e32 v4, 3, v6
	v_mov_b32_e32 v5, v145
	v_lshl_add_u64 v[0:1], s[4:5], 0, v[0:1]
	s_lshl_b32 s29, s2, 5
	s_lshl_b64 s[0:1], s[84:85], 2
	v_lshl_add_u64 v[42:43], v[0:1], 0, v[4:5]
	v_or_b32_e32 v0, v7, v121
	s_waitcnt lgkmcnt(0)
	s_add_u32 s0, s74, s0
	v_lshlrev_b32_e32 v51, 2, v0
	v_or_b32_e32 v0, 16, v121
	v_or_b32_e32 v55, 32, v121
	v_and_b32_e32 v144, 48, v120
	s_addc_u32 s1, s75, s1
	v_or_b32_e32 v1, v7, v0
	v_lshlrev_b32_e32 v50, 4, v0
	v_or_b32_e32 v0, v7, v55
	v_lshl_add_u64 v[38:39], s[0:1], 0, v[144:145]
	v_lshl_add_u64 v[40:41], v[2:3], 0, v[4:5]
	v_mov_b32_e32 v2, s30
	s_movk_i32 s0, 0x90
	v_lshlrev_b32_e32 v94, 2, v0
	v_or_b32_e32 v0, v7, v176
	v_mad_u32_u24 v49, v120, s0, v2
	s_movk_i32 s0, 0x110
	v_lshlrev_b32_e32 v53, 2, v1
	v_lshlrev_b32_e32 v95, 2, v0
	v_lshlrev_b32_e32 v0, 8, v121
	v_mov_b32_e32 v1, v145
	v_mad_u32_u24 v10, v121, s0, v2
	v_lshl_add_u64 v[2:3], s[70:71], 0, v[0:1]
	v_lshl_add_u64 v[0:1], s[72:73], 0, v[0:1]
	v_lshlrev_b32_e32 v8, 2, v121
	v_mul_i32_i24_e32 v9, 0xffffff74, v120
	v_lshl_add_u64 v[58:59], v[0:1], 0, v[144:145]
	v_mul_u32_u24_e32 v0, 0x240, v6
	v_lshl_add_u64 v[32:33], s[66:67], 0, v[144:145]
	v_lshl_add_u64 v[34:35], s[68:69], 0, v[144:145]
	v_lshl_add_u64 v[44:45], s[34:35], 0, v[4:5]
	v_lshl_add_u64 v[46:47], s[4:5], 0, v[4:5]
	v_lshlrev_b32_e32 v48, 4, v121
	v_lshlrev_b32_e32 v52, 4, v55
	v_lshlrev_b32_e32 v54, 4, v176
	v_lshl_add_u64 v[56:57], v[2:3], 0, v[144:145]
	v_add3_u32 v96, s30, v8, v0
	v_or_b32_e32 v97, 48, v121
	v_add_u32_e32 v98, v49, v9
	v_add_u32_e32 v99, v10, v125
	s_branch .LBB0_891
